# XCD-local barriers after P1, P6, P7 (producer and consumer rows live on one XCD): the last arriver of an XCD releases its waiters without L2 write-back / top level; runtime check xcc_id==bx%8 with fal
# speedup vs baseline: 1.0113x; 1.0056x over previous
_Z10fwd_kernel6Params:
	s_mov_b64 s[94:95], s[0:1]
	s_mov_b32 s100, 0
	s_mov_b32 s101, 0
	s_load_dwordx4 s[44:47], s[0:1], 0xc8
	s_load_dword s48, s[0:1], 0xd8
	s_add_u32 s0, s94, 0xd8
	s_addc_u32 s1, s95, 0
	v_readfirstlane_b32 s33, v0
	v_writelane_b32 v251, s0, 0
	v_cmp_gt_u32_e32 vcc, 64, v0
	s_nop 0
	v_writelane_b32 v251, s1, 1
	s_and_saveexec_b64 s[0:1], vcc
	v_lshl_add_u32 v1, v0, 2, 0
	v_add_u32_e32 v1, 0x27c00, v1
	v_mov_b32_e32 v2, 0
	ds_write_b32 v1, v2
	s_or_b64 exec, exec, s[0:1]
	s_waitcnt lgkmcnt(0)
	s_barrier
	s_getreg_b32 s3, hwreg(HW_REG_XCC_ID, 0, 4)
	s_mov_b32 s11, 0
	v_cmp_eq_u32_e32 vcc, 0, v0
	s_and_saveexec_b64 s[0:1], vcc
	s_cbranch_execz .LBB0_5
	s_mov_b64 s[4:5], exec
	v_mbcnt_lo_u32_b32 v0, s4, 0
	v_mbcnt_hi_u32_b32 v0, s5, v0
	v_cmp_eq_u32_e32 vcc, 0, v0
	s_and_b64 s[6:7], exec, vcc
	s_mov_b64 exec, s[6:7]
	s_cbranch_execz .LBB0_5
	s_lshl_b32 s3, s3, 8
	s_and_b32 s3, s3, 0xf00
	s_bcnt1_i32_b64 s4, s[4:5]
	v_mov_b32_e32 v0, s3
	v_mov_b32_e32 v1, s4
	global_atomic_add v0, v1, s[46:47] offset:1024
	s_lshr_b32 s6, s3, 8
	s_and_b32 s7, s2, 7
	s_cmp_eq_u32 s6, s7
	s_cbranch_scc1 .LBB0_5
	v_mov_b32_e32 v0, 0x280
	global_atomic_add v0, v1, s[46:47]

.LBB0_181:
	s_lshl_b32 s24, s38, 6
	s_add_i32 s6, s24, 0x500
	s_mov_b32 s7, 0
	s_lshl_b64 s[4:5], s[6:7], 2
	s_add_u32 s4, s36, s4
	s_addc_u32 s5, s37, s5
	v_mov_b32_e32 v1, 1
	v_mov_b64_e32 v[4:5], s[4:5]
	flat_atomic_add v1, v[4:5], v1 sc0
	v_cvt_f32_u32_e32 v3, v2
	v_sub_u32_e32 v4, 0, v2
	v_rcp_iflag_f32_e32 v3, v3
	s_nop 0
	v_mul_f32_e32 v3, 0x4f7ffffe, v3
	v_cvt_u32_f32_e32 v3, v3
	v_mul_lo_u32 v4, v4, v3
	v_mul_hi_u32 v4, v3, v4
	v_add_u32_e32 v3, v3, v4
	s_waitcnt vmcnt(0) lgkmcnt(0)
	v_mul_hi_u32 v3, v1, v3
	v_mul_lo_u32 v5, v3, v2
	v_add_u32_e32 v4, 1, v1
	v_sub_u32_e32 v1, v1, v5
	v_add_u32_e32 v6, 1, v3
	v_cmp_ge_u32_e32 vcc, v1, v2
	v_sub_u32_e32 v5, v1, v2
	s_nop 0
	v_cndmask_b32_e32 v3, v3, v6, vcc
	v_cndmask_b32_e32 v1, v1, v5, vcc
	v_add_u32_e32 v5, 1, v3
	v_cmp_ge_u32_e32 vcc, v1, v2
	s_nop 1
	v_cndmask_b32_e32 v1, v3, v5, vcc
	v_mad_u64_u32 v[2:3], s[4:5], v2, v1, v[2:3]
	v_cmp_ne_u32_e32 vcc, v4, v2
	s_and_saveexec_b64 s[4:5], vcc
	s_xor_b64 s[4:5], exec, s[4:5]
	s_cbranch_execz .LBB0_194
	s_add_i32 s6, s24, 0x900
	s_lshl_b64 s[6:7], s[6:7], 2
	s_add_u32 s8, s36, 0x3400
	s_addc_u32 s9, s37, 0
	v_mov_b32_e32 v4, s101
	v_mad_u32_u24 v4, v4, v0, v0
	s_add_i32 s101, s101, 1
	v_mov_b64_e32 v[2:3], s[8:9]
	flat_load_dword v0, v[2:3] sc1
	s_waitcnt vmcnt(0) lgkmcnt(0)
	v_cmp_lt_u32_e32 vcc, v0, v4
	s_and_saveexec_b64 s[6:7], vcc
	s_cbranch_execz .LBB0_193
	s_mov_b32 s25, 1
	s_mov_b64 s[10:11], 0
	s_branch .LBB0_185

.LBB0_194:
	s_andn2_saveexec_b64 s[4:5], s[4:5]
	s_cbranch_execz .LBB0_210
	s_add_i32 s101, s101, 1
	v_mov_b32_e32 v1, s36
	v_add_co_u32_e32 v2, vcc, 0x3000, v1
	v_mov_b32_e32 v1, s37
	buffer_wbl2 sc1
	s_waitcnt vmcnt(0)
	v_addc_co_u32_e32 v3, vcc, 0, v1, vcc
	v_mov_b32_e32 v1, 1
	flat_atomic_add v1, v[2:3], v1 offset:1024 sc0
	v_cvt_f32_u32_e32 v2, v0
	v_sub_u32_e32 v3, 0, v0
	s_add_u32 s4, s36, 0x3400
	s_addc_u32 s5, s37, 0
	v_rcp_iflag_f32_e32 v2, v2
	s_mov_b64 s[8:9], -1
	v_mul_f32_e32 v2, 0x4f7ffffe, v2
	v_cvt_u32_f32_e32 v2, v2
	v_mul_lo_u32 v3, v3, v2
	v_mul_hi_u32 v3, v2, v3
	v_add_u32_e32 v2, v2, v3
	s_waitcnt vmcnt(0) lgkmcnt(0)
	v_mul_hi_u32 v2, v1, v2
	v_mul_lo_u32 v4, v2, v0
	v_add_u32_e32 v3, 1, v1
	v_sub_u32_e32 v1, v1, v4
	v_add_u32_e32 v5, 1, v2
	v_cmp_ge_u32_e32 vcc, v1, v0
	v_sub_u32_e32 v4, v1, v0
	s_nop 0
	v_cndmask_b32_e32 v2, v2, v5, vcc
	v_cndmask_b32_e32 v1, v1, v4, vcc
	v_add_u32_e32 v4, 1, v2
	v_cmp_ge_u32_e32 vcc, v1, v0
	s_nop 1
	v_cndmask_b32_e32 v2, v2, v4, vcc
	v_mad_u64_u32 v[0:1], s[6:7], v0, v2, v[0:1]
	v_cmp_ne_u32_e32 vcc, v3, v0
	v_mov_b32_e32 v3, v0
	v_mov_b64_e32 v[0:1], s[4:5]
	s_and_saveexec_b64 s[6:7], vcc
	s_cbranch_execz .LBB0_207
	v_mov_b64_e32 v[0:1], s[4:5]
	flat_load_dword v0, v[0:1] sc1
	s_mov_b64 s[12:13], 0
	s_waitcnt vmcnt(0) lgkmcnt(0)
	v_cmp_lt_u32_e32 vcc, v0, v3
	s_and_saveexec_b64 s[10:11], vcc
	s_cbranch_execz .LBB0_206
	s_add_u32 s8, s36, 0x200
	s_addc_u32 s9, s37, 0
	s_mov_b32 s25, 1
	s_branch .LBB0_199

.LBB0_210:
	s_or_b64 exec, exec, s[0:1]
	v_mov_b32_e32 v235, 0
	global_load_dword v234, v235, s[46:47] offset:640 sc1
	s_waitcnt vmcnt(0)
	v_readfirstlane_b32 s100, v234
	s_cmp_eq_u32 s100, 0
	s_cselect_b32 s100, 1, 0
	s_lshl_b32 s22, s2, 3
	s_add_i32 s28, s60, s22
	s_lshl_b32 s80, s48, 3
	s_cmpk_gt_i32 s28, 0x9ff
	s_cselect_b64 s[0:1], -1, 0
	v_writelane_b32 v251, s0, 5
	s_cmpk_lg_i32 s48, 0x100
	s_mov_b32 s83, 0
	v_writelane_b32 v251, s1, 6
	s_cselect_b64 s[0:1], -1, 0
	v_writelane_b32 v251, s0, 7
	s_cmpk_lt_i32 s28, 0x4000
	s_mov_b32 s37, s83
	v_writelane_b32 v251, s1, 8
	s_cselect_b64 s[0:1], -1, 0
	v_writelane_b32 v251, s0, 9
	s_mov_b32 s39, s83
	s_mov_b32 s41, s83
	v_writelane_b32 v251, s1, 10
	s_and_b32 s1, s2, 0x1ffffff8
	s_lshl_b32 s0, s2, 11
	s_add_i32 s1, s60, s1
	s_and_b32 s0, s0, 0x3800
	s_lshl_b32 s1, s1, 3
	s_add_i32 s20, s1, s0
	s_or_b32 s18, s20, 1
	s_ashr_i32 s21, s20, 31
	s_add_i32 s30, s20, 0xffffe000
	s_ashr_i32 s19, s18, 31
	s_cmpk_gt_i32 s18, 0x1fff
	s_cselect_b64 s[0:1], -1, 0
	s_or_b32 s16, s20, 2
	s_add_i32 s34, s20, 0xffffe001
	s_ashr_i32 s17, s16, 31
	v_writelane_b32 v251, s0, 11
	s_cmpk_gt_i32 s16, 0x1fff
	s_mov_b32 s43, s83
	v_writelane_b32 v251, s1, 12
	s_cselect_b64 s[0:1], -1, 0
	s_or_b32 s14, s20, 3
	s_add_i32 s36, s20, 0xffffe002
	s_ashr_i32 s15, s14, 31
	v_writelane_b32 v251, s0, 13
	s_cmpk_gt_i32 s14, 0x1fff
	s_mov_b32 s51, s83
	v_writelane_b32 v251, s1, 14
	s_cselect_b64 s[0:1], -1, 0
	s_or_b32 s12, s20, 4
	s_add_i32 s38, s20, 0xffffe003
	s_ashr_i32 s13, s12, 31
	v_writelane_b32 v251, s0, 15
	s_cmpk_gt_i32 s12, 0x1fff
	s_mov_b32 s65, s83
	v_writelane_b32 v251, s1, 16
	s_cselect_b64 s[0:1], -1, 0
	s_or_b32 s10, s20, 5
	s_add_i32 s40, s20, 0xffffe004
	s_ashr_i32 s11, s10, 31
	v_writelane_b32 v251, s0, 17
	s_cmpk_gt_i32 s10, 0x1fff
	s_mov_b32 s57, s83
	v_writelane_b32 v251, s1, 18
	s_cselect_b64 s[0:1], -1, 0
	s_or_b32 s8, s20, 6
	s_add_i32 s42, s20, 0xffffe005
	s_ashr_i32 s9, s8, 31
	v_writelane_b32 v251, s0, 19
	s_cmpk_gt_i32 s8, 0x1fff
	s_mov_b32 s69, s83
	v_writelane_b32 v251, s1, 20
	s_cselect_b64 s[0:1], -1, 0
	s_or_b32 s54, s20, 7
	v_writelane_b32 v251, s0, 21
	s_ashr_i32 s55, s54, 31
	s_add_i32 s50, s20, 0xffffe006
	v_writelane_b32 v251, s1, 22
	s_lshl_b64 s[0:1], s[54:55], 12
	v_writelane_b32 v251, s0, 23
	s_cmpk_gt_i32 s54, 0x1fff
	s_mov_b32 s67, s83
	v_writelane_b32 v251, s1, 24
	s_cselect_b64 s[0:1], -1, 0
	v_writelane_b32 v251, s0, 25
	s_add_i32 s82, s20, 0xffffe007
	s_mov_b32 s73, s83
	v_writelane_b32 v251, s1, 26
	s_lshl_b64 s[0:1], s[82:83], 12
	v_writelane_b32 v251, s0, 27
	s_mov_b32 s75, s83
	v_mov_b32_e32 v9, 0
	v_writelane_b32 v251, s1, 28
	s_lshr_b32 s0, s30, 10
	s_add_i32 s4, s0, 1
	s_cmpk_gt_i32 s20, 0x1fff
	s_cselect_b64 s[0:1], -1, 0
	v_writelane_b32 v251, s0, 29
	v_mov_b32_e32 v236, 0x358637bd
	v_mov_b32_e32 v237, 0x260
	v_writelane_b32 v251, s1, 30
	s_and_b64 s[0:1], s[0:1], exec
	v_writelane_b32 v251, s20, 31
	s_cselect_b32 s6, s4, 0
	s_lshl_b64 s[0:1], s[20:21], 11
	v_writelane_b32 v251, s21, 32
	v_writelane_b32 v251, s0, 33
	s_lshr_b32 s85, s33, 8
	s_bfe_u32 s61, s33, 0x20006
	v_writelane_b32 v251, s1, 34
	v_writelane_b32 v251, s18, 35
	s_lshl_b64 s[0:1], s[18:19], 11
	s_lshl_b32 s76, s60, 10
	v_writelane_b32 v251, s19, 36
	v_writelane_b32 v251, s0, 37
	v_mov_b32_e32 v228, 1
	v_mov_b64_e32 v[180:181], 0x3ff
	v_writelane_b32 v251, s1, 38
	v_writelane_b32 v251, s16, 39
	s_lshl_b64 s[0:1], s[16:17], 11
	v_mov_b32_e32 v242, 0x3ffffffe
	v_writelane_b32 v251, s17, 40
	v_writelane_b32 v251, s0, 41
	s_mul_i32 s17, s85, 0x4400
	v_mov_b32_e32 v243, 0x3ffffffc
	v_writelane_b32 v251, s1, 42
	v_writelane_b32 v251, s14, 43
	s_lshl_b64 s[0:1], s[14:15], 11
	v_mov_b32_e32 v244, 0x3ffffff8
	v_writelane_b32 v251, s15, 44
	v_writelane_b32 v251, s0, 45
	v_mov_b32_e32 v245, 0x3ffffff0
	v_mov_b32_e32 v246, 0x3fffffe0
	v_writelane_b32 v251, s1, 46
	v_writelane_b32 v251, s12, 47
	s_lshl_b64 s[0:1], s[12:13], 11
	v_mov_b64_e32 v[182:183], 0x555
	v_writelane_b32 v251, s13, 48
	v_writelane_b32 v251, s0, 49
	v_mov_b32_e32 v247, 0x42800000
	v_not_b32_e32 v248, 63
	v_writelane_b32 v251, s1, 50
	v_writelane_b32 v251, s10, 51
	s_lshl_b64 s[0:1], s[10:11], 11
	v_mov_b32_e32 v241, 0xf149f2ca
	v_writelane_b32 v251, s11, 52
	v_writelane_b32 v251, s0, 53
	v_mov_b64_e32 v[184:185], 0x100
	v_mov_b64_e32 v[186:187], 0xff
	v_writelane_b32 v251, s1, 54
	v_writelane_b32 v251, s8, 55
	s_lshl_b64 s[0:1], s[8:9], 11
	s_mov_b32 s92, 0xf800000
	v_writelane_b32 v251, s9, 56
	v_writelane_b32 v251, s0, 57
	s_mov_b32 s89, 0x41000000
	s_mov_b32 s77, 0x8c58000
	v_writelane_b32 v251, s1, 58
	s_lshl_b32 s0, s85, 6
	v_writelane_b32 v251, s0, 59
	s_lshl_b32 s0, s85, 13
	v_writelane_b32 v251, s0, 60
	s_lshl_b32 s1, s61, 5
	s_lshl_b32 s0, s61, 12
	s_cmpk_lt_i32 s2, 0x400
	v_writelane_b32 v251, s0, 61
	s_cselect_b64 s[4:5], -1, 0
	s_lshr_b32 s0, s3, 29
	s_add_i32 s0, s2, s0
	s_ashr_i32 s18, s0, 3
	s_and_b32 s0, s0, -8
	s_sub_i32 s23, s2, s0
	s_lshl_b32 s24, s23, 7
	s_add_i32 s62, s76, 0
	v_writelane_b32 v251, s4, 62
	s_cmp_eq_u32 s85, 1
	s_mov_b64 s[86:87], 0x80
	v_writelane_b32 v251, s5, 63
	s_cselect_b64 s[4:5], -1, 0
	v_writelane_b32 v252, s4, 0
	s_cmpk_lt_u32 s33, 0x100
	s_waitcnt lgkmcnt(0)
	v_writelane_b32 v252, s5, 1
	s_cselect_b64 s[4:5], -1, 0
	s_bfe_u32 s56, s60, 0x10001
	s_or_b32 s66, s56, 2
	s_and_b32 s0, s1, 32
	s_lshl_b32 s64, s56, 6
	s_lshl_b32 s68, s66, 6
	v_writelane_b32 v252, s1, 2
	s_cmp_lg_u32 s61, 0
	v_writelane_b32 v252, s0, 3
	s_cselect_b64 s[0:1], -1, 0
	v_writelane_b32 v252, s0, 4
	s_cmp_gt_u32 s61, 1
	s_barrier
	v_writelane_b32 v252, s1, 5
	s_cselect_b64 s[0:1], -1, 0
	v_writelane_b32 v252, s0, 6
	s_cmp_lt_u32 s61, 2
	s_nop 0
	v_writelane_b32 v252, s1, 7
	s_cselect_b64 s[0:1], -1, 0
	v_writelane_b32 v252, s0, 8
	s_nop 1
	v_writelane_b32 v252, s1, 9
	v_sub_co_u32_e64 v0, s[0:1], s61, 2
	s_nop 0
	v_readfirstlane_b32 s8, v0
	v_writelane_b32 v252, s0, 10
	s_nop 1
	v_writelane_b32 v252, s1, 11
	s_and_b64 s[0:1], s[0:1], exec
	s_mov_b32 s0, 0x1000000
	s_cselect_b32 s0, s0, 0x1200000
	s_lshl_b32 s1, s2, 4
	s_and_b32 s29, s1, 0xffffffc0
	s_and_b32 s20, s1, 0x3c0
	s_bfe_i32 s1, s2, 0x1001b
	s_lshr_b32 s1, s1, 24
	s_add_i32 s1, s29, s1
	s_ashr_i32 s9, s8, 31
	s_and_b32 s1, s1, 0xffffff00
	v_writelane_b32 v252, s8, 12
	s_sub_i32 s21, s29, s1
	s_lshl_b32 s1, s2, 6
	v_writelane_b32 v252, s9, 13
	s_and_b32 s1, s1, 0xc0
	v_writelane_b32 v252, s1, 14
	s_lshl_b32 s1, s61, 6
	s_and_b32 s7, s1, 64
	v_writelane_b32 v252, s7, 15
	s_add_i32 s7, s62, 0x21c00
	v_writelane_b32 v252, s7, 16
	s_add_i32 s7, s62, 0x23c00
	v_writelane_b32 v252, s7, 17
	s_add_i32 s7, s62, 0x25c00
	s_lshl_b32 s8, s60, 1
	v_writelane_b32 v252, s7, 18
	s_cmpk_lt_u32 s33, 0x200
	s_mul_hi_u32 s7, s8, 0xcccccccd
	s_cselect_b64 s[10:11], -1, 0
	s_lshr_b32 s9, s7, 2
	v_writelane_b32 v252, s10, 19
	s_mul_i32 s7, s9, 5
	s_sub_i32 s7, s8, s7
	v_writelane_b32 v252, s11, 20
	s_or_b32 s10, s8, 1
	s_lshl_b32 s72, s9, 8
	s_cmp_lt_u32 s10, 15
	s_mul_hi_u32 s8, s10, 0xcccccccd
	s_cselect_b64 s[12:13], -1, 0
	s_lshr_b32 s9, s8, 2
	s_mul_i32 s8, s9, 5
	v_writelane_b32 v252, s12, 21
	s_sub_i32 s8, s10, s8
	s_lshl_b32 s10, s10, 8
	s_lshl_b32 s74, s9, 8
	s_and_b32 s9, s33, 0xc0
	v_writelane_b32 v252, s13, 22
	s_cmpk_eq_i32 s9, 0xc0
	v_writelane_b32 v252, s10, 23
	s_cselect_b64 s[10:11], -1, 0
	v_writelane_b32 v252, s10, 24
	s_lshl_b32 s9, s85, 5
	s_add_i32 s93, s17, 0
	v_writelane_b32 v252, s11, 25
	s_lshl_b32 s10, s61, 3
	s_or_b32 s9, s10, s9
	s_and_b32 s10, s2, 3
	s_and_b32 s11, s60, 0x3fffffc
	v_writelane_b32 v252, s11, 26
	s_or_b32 s10, s11, s10
	v_writelane_b32 v252, s10, 27
	s_mul_i32 s10, s85, 0xba00
	s_add_i32 s63, s10, 0
	s_lshl_b32 s10, s9, 1
	s_add_i32 s10, s10, 0
	v_writelane_b32 v252, s10, 28
	s_or_b32 s10, s9, 1
	s_or_b32 s11, s9, 2
	s_or_b32 s12, s9, 3
	s_or_b32 s13, s9, 4
	s_or_b32 s14, s9, 5
	s_or_b32 s15, s9, 6
	s_or_b32 s16, s9, 7
	s_sub_i32 s17, 56, s9
	s_sub_i32 s10, 63, s10
	s_sub_i32 s11, 63, s11
	s_sub_i32 s12, 63, s12
	s_sub_i32 s13, 63, s13
	s_sub_i32 s14, 63, s14
	s_sub_i32 s15, 63, s15
	s_sub_i32 s16, 63, s16
	s_add_i32 s88, s63, 0x8800
	v_writelane_b32 v252, s17, 29
	s_sub_i32 s17, 63, s9
	s_cmp_eq_u32 s61, 3
	s_cselect_b64 s[26:27], -1, 0
	v_writelane_b32 v252, s26, 30
	s_cmp_lg_u32 s61, 3
	s_nop 0
	v_writelane_b32 v252, s27, 31
	s_cselect_b64 s[26:27], -1, 0
	v_writelane_b32 v252, s26, 32
	s_cmp_eq_u32 s61, s85
	s_nop 0
	v_writelane_b32 v252, s27, 33
	s_cselect_b64 s[26:27], -1, 0
	v_writelane_b32 v252, s26, 34
	s_lshl_b32 s19, s61, 10
	s_lshl_b32 s59, s60, 5
	v_writelane_b32 v252, s27, 35
	s_lshl_b32 s84, s61, 4
	v_writelane_b32 v252, s19, 36
	s_or_b32 s19, s59, 16
	s_bfe_u32 s31, s33, 0x10008
	s_cmp_eq_u32 s31, 0
	v_writelane_b32 v252, s19, 37
	s_cselect_b64 s[90:91], -1, 0
	s_bfe_i32 s19, s60, 0x10000
	s_and_b32 s58, s19, 24
	s_lshl_b32 s19, s61, 8
	s_or_b32 s25, s19, 64
	v_writelane_b32 v252, s25, 38
	s_or_b32 s25, s19, 0x80
	v_writelane_b32 v252, s25, 39
	v_writelane_b32 v252, s19, 40
	s_or_b32 s19, s19, 0xc0
	s_and_b32 s70, s59, 32
	v_writelane_b32 v252, s19, 41
	s_or_b32 s19, s70, 16
	v_writelane_b32 v252, s19, 42
	s_min_u32 s19, s19, 40
	s_add_i32 s25, s19, -8
	s_lshl_b32 s35, s60, 3
	s_cmp_eq_u32 s61, 0
	v_writelane_b32 v252, s25, 43
	s_cselect_b64 s[26:27], -1, 0
	v_writelane_b32 v252, s26, 44
	s_nop 1
	v_writelane_b32 v252, s27, 45
	s_and_b64 s[26:27], s[26:27], exec
	s_cselect_b32 s25, 0, 0x2400
	s_add_i32 s25, s63, s25
	v_writelane_b32 v252, s25, 46
	s_or_b32 s25, s35, 4
	v_writelane_b32 v252, s35, 47
	s_cmpk_lt_i32 s2, 0x100
	v_writelane_b32 v252, s25, 48
	s_cselect_b64 s[26:27], -1, 0
	s_and_b32 s22, s22, 56
	s_ashr_i32 s25, s2, 5
	s_add_i32 s22, s22, s25
	s_lshl_b32 s22, s22, 2
	s_bfe_u32 s25, s2, 0x20003
	s_or_b32 s22, s22, s25
	v_writelane_b32 v252, s26, 49
	s_cmpk_eq_i32 s48, 0x100
	s_mov_b32 s35, s83
	v_writelane_b32 v252, s27, 50
	s_cselect_b64 s[26:27], -1, 0
	v_writelane_b32 v252, s26, 51
	s_nop 1
	v_writelane_b32 v252, s27, 52
	s_and_b64 s[26:27], s[26:27], exec
	v_writelane_b32 v252, s22, 53
	s_cselect_b32 s22, s22, s2
	s_and_b32 s25, s22, 3
	s_ashr_i32 s78, s22, 2
	s_and_b32 s22, s33, 0xffffff00
	s_or_b32 s22, s1, s22
	v_writelane_b32 v252, s22, 54
	v_writelane_b32 v252, s25, 55
	s_lshl_b32 s22, s25, 19
	v_writelane_b32 v252, s22, 56
	s_and_b32 s22, s59, 0x60
	v_writelane_b32 v252, s22, 57
	s_lshr_b32 s22, s22, 3
	v_writelane_b32 v252, s22, 58
	s_mov_b32 s26, s78
	s_ashr_i32 s79, s78, 31
	v_writelane_b32 v252, s26, 59
	s_lshl_b32 s22, s23, 5
	s_mul_i32 s25, s23, 0x81
	v_writelane_b32 v252, s27, 60
	s_lshl_b64 s[26:27], s[78:79], 19
	s_cmp_lt_i32 s23, 0
	s_cselect_b32 s24, s25, s24
	s_mul_i32 s23, s23, 33
	s_cselect_b32 s25, s23, s22
	s_add_i32 s22, s24, s18
	s_ashr_i32 s23, s22, 31
	s_lshr_b32 s23, s23, 25
	s_add_i32 s23, s22, s23
	s_and_b32 s24, s23, 0xff80
	s_sub_i32 s22, s22, s24
	s_bfe_i32 s24, s22, 0x80000
	s_bfe_u32 s24, s24, 0x3000c
	v_writelane_b32 v252, s26, 61
	s_add_i32 s24, s22, s24
	s_ashr_i32 s23, s23, 7
	v_writelane_b32 v252, s27, 62
	s_and_b32 s26, s24, 0xf8
	s_sub_i32 s22, s22, s26
	s_bfe_i32 s24, s24, 0x80000
	s_lshl_b32 s23, s23, 3
	s_sext_i32_i16 s24, s24
	s_sext_i32_i8 s22, s22
	s_add_i32 s26, s23, s22
	s_ashr_i32 s22, s24, 3
	v_writelane_b32 v252, s22, 63
	s_lshr_b32 s22, s24, 3
	s_bfe_i64 s[22:23], s[22:23], 0x100000
	s_lshl_b64 s[22:23], s[22:23], 19
	v_writelane_b32 v253, s22, 0
	s_ashr_i32 s27, s26, 31
	s_mov_b32 s33, 0xc2fc0000
	v_writelane_b32 v253, s23, 1
	s_mov_b32 s22, s26
	v_writelane_b32 v253, s22, 2
	s_mov_b32 s78, 0x8c60000
	s_nop 0
	v_writelane_b32 v253, s23, 3
	s_lshl_b64 s[22:23], s[26:27], 19
	s_cmpk_lt_i32 s29, 0x2000
	v_writelane_b32 v253, s22, 4
	s_cselect_b32 s20, s21, s20
	s_movk_i32 s21, 0x400
	v_writelane_b32 v253, s23, 5
	s_cselect_b32 s21, 0x100, s21
	s_add_i32 s18, s25, s18
	v_writelane_b32 v253, s21, 6
	s_ashr_i32 s21, s18, 31
	s_lshr_b32 s21, s21, 27
	s_add_i32 s21, s18, s21
	s_and_b32 s22, s21, 0xffe0
	s_sub_i32 s18, s18, s22
	s_bfe_i32 s22, s18, 0x80000
	s_bfe_u32 s22, s22, 0x3000c
	s_add_i32 s22, s18, s22
	s_and_b32 s23, s22, 0xf8
	s_sub_i32 s18, s18, s23
	s_lshl_b32 s23, s2, 5
	s_lshl_b32 s24, s60, 2
	s_add_i32 s23, s23, s24
	v_writelane_b32 v253, s23, 7
	s_lshl_b32 s23, s2, 9
	s_lshl_b32 s24, s60, 6
	s_add_i32 s23, s23, s24
	v_writelane_b32 v253, s23, 8
	v_writelane_b32 v253, s29, 9
	s_sub_i32 s23, s29, s20
	v_writelane_b32 v253, s23, 10
	s_add_i32 s20, s20, -2
	v_writelane_b32 v253, s20, 11
	s_ashr_i32 s20, s21, 5
	s_bfe_i32 s21, s22, 0x80000
	s_lshl_b32 s20, s20, 3
	s_sext_i32_i16 s21, s21
	s_sext_i32_i8 s18, s18
	s_add_i32 s24, s20, s18
	s_ashr_i32 s18, s21, 3
	v_writelane_b32 v253, s18, 12
	s_lshr_b32 s18, s21, 3
	s_bfe_i64 s[20:21], s[18:19], 0x100000
	s_lshl_b64 s[20:21], s[20:21], 19
	s_mul_i32 s18, s9, 0x180
	v_writelane_b32 v253, s20, 13
	s_add_i32 s18, s18, 0
	s_add_i32 s18, s18, 0x1fc00
	v_writelane_b32 v253, s21, 14
	v_writelane_b32 v253, s18, 15
	v_writelane_b32 v253, s31, 16
	s_lshl_b32 s18, s31, 12
	v_writelane_b32 v253, s18, 17
	s_lshl_b32 s18, s48, 5
	v_writelane_b32 v253, s18, 18
	s_add_i32 s18, s28, 0xfffff800
	v_writelane_b32 v253, s18, 19
	s_lshl_b32 s18, s48, 9
	v_writelane_b32 v253, s18, 20
	s_lshl_b32 s18, s2, 1
	v_writelane_b32 v253, s18, 21
	s_lshl_b32 s18, s48, 1
	v_writelane_b32 v253, s18, 22
	s_mov_b32 s22, s24
	s_ashr_i32 s25, s24, 31
	v_writelane_b32 v253, s22, 23
	s_ashr_i32 s29, s28, 31
	s_ashr_i32 s81, s80, 31
	v_writelane_b32 v253, s23, 24
	s_lshl_b64 s[22:23], s[24:25], 19
	v_writelane_b32 v253, s22, 25
	s_mul_i32 s18, s2, 0x3000
	s_mul_i32 s20, s85, 0x1800
	v_writelane_b32 v253, s23, 26
	v_writelane_b32 v253, s28, 27
	s_lshl_b64 s[22:23], s[28:29], 12
	s_mov_b32 s31, s83
	v_writelane_b32 v253, s29, 28
	v_writelane_b32 v253, s22, 29
	s_nop 1
	v_writelane_b32 v253, s23, 30
	s_lshl_b64 s[22:23], s[80:81], 12
	v_writelane_b32 v253, s22, 31
	s_add_u32 s18, s18, s20
	s_mul_hi_u32 s20, s85, 0x1800
	v_writelane_b32 v253, s23, 32
	v_writelane_b32 v253, s18, 33
	s_mul_hi_i32 s18, s2, 0x3000
	s_addc_u32 s18, s18, s20
	s_lshl_b64 s[20:21], s[2:3], 1
	s_add_u32 s20, s85, s20
	v_writelane_b32 v253, s18, 34
	s_addc_u32 s21, 0, s21
	v_writelane_b32 v253, s20, 35
	s_mul_hi_u32 s18, s6, 0x3000
	s_mulk_i32 s6, 0x3000
	v_writelane_b32 v253, s21, 36
	v_writelane_b32 v253, s30, 37
	s_lshl_b32 s0, s0, 2
	s_nop 0
	v_writelane_b32 v253, s31, 38
	v_writelane_b32 v253, s34, 39
	s_nop 1
	v_writelane_b32 v253, s35, 40
	v_writelane_b32 v253, s36, 41
	s_nop 1
	v_writelane_b32 v253, s37, 42
	v_writelane_b32 v253, s38, 43
	s_nop 1
	v_writelane_b32 v253, s39, 44
	v_writelane_b32 v253, s40, 45
	s_nop 1
	v_writelane_b32 v253, s41, 46
	v_writelane_b32 v253, s42, 47
	s_nop 1
	v_writelane_b32 v253, s43, 48
	v_writelane_b32 v253, s50, 49
	s_nop 1
	v_writelane_b32 v253, s51, 50
	v_writelane_b32 v253, s54, 51
	s_mov_b32 s82, s54
	s_nop 0
	v_writelane_b32 v253, s55, 52
	v_writelane_b32 v253, s18, 53
	v_writelane_b32 v253, s6, 54
	v_writelane_b32 v253, s64, 55
	s_mul_i32 s6, s7, 0x300
	s_mov_b32 s7, s83
	v_writelane_b32 v253, s65, 56
	v_writelane_b32 v253, s56, 57
	s_movk_i32 s64, 0x600
	s_nop 0
	v_writelane_b32 v253, s57, 58
	v_writelane_b32 v253, s68, 59
	s_nop 1
	v_writelane_b32 v253, s69, 60
	v_writelane_b32 v253, s66, 61
	s_nop 1
	v_writelane_b32 v253, s67, 62
	v_writelane_b32 v253, s6, 63
	s_mov_b32 s66, 0x8c48000
	s_mov_b32 s67, 0x8c50000
	v_writelane_b32 v254, s7, 0
	v_writelane_b32 v254, s72, 1
	s_mul_i32 s6, s8, 0x300
	s_mov_b32 s7, s83
	v_writelane_b32 v254, s73, 2
	v_writelane_b32 v254, s6, 3
	s_mov_b32 s72, 0x2aaaaaab
	s_movk_i32 s73, 0x110
	v_writelane_b32 v254, s7, 4
	v_writelane_b32 v254, s74, 5
	s_mul_i32 s6, s9, 0x90
	s_nop 0
	v_writelane_b32 v254, s75, 6
	v_writelane_b32 v254, s6, 7
	s_mul_i32 s6, s17, 0x90
	v_writelane_b32 v254, s6, 8
	s_mul_i32 s6, s10, 0x90
	v_writelane_b32 v254, s6, 9
	s_mul_i32 s6, s11, 0x90
	v_writelane_b32 v254, s6, 10
	s_mul_i32 s6, s12, 0x90
	v_writelane_b32 v254, s6, 11
	s_mul_i32 s6, s13, 0x90
	v_writelane_b32 v254, s6, 12
	s_mul_i32 s6, s14, 0x90
	v_writelane_b32 v254, s6, 13
	s_mul_i32 s6, s15, 0x90
	v_writelane_b32 v254, s6, 14
	s_mul_i32 s6, s16, 0x90
	v_writelane_b32 v254, s6, 15
	s_sub_i32 s6, s19, s70
	s_sub_i32 s7, s6, 17
	v_writelane_b32 v254, s7, 16
	s_sub_i32 s7, s6, 18
	v_writelane_b32 v254, s7, 17
	s_sub_i32 s7, s6, 19
	v_writelane_b32 v254, s7, 18
	s_sub_i32 s7, s6, 20
	v_writelane_b32 v254, s7, 19
	s_sub_i32 s7, s6, 21
	v_writelane_b32 v254, s7, 20
	s_sub_i32 s7, s6, 22
	v_writelane_b32 v254, s7, 21
	s_sub_i32 s7, s6, 23
	v_writelane_b32 v254, s7, 22
	s_sub_i32 s6, s6, 24
	v_writelane_b32 v254, s6, 23
	v_writelane_b32 v254, s0, 24
	s_lshl_b32 s0, s1, 1
	v_writelane_b32 v254, s0, 25
	s_mov_b32 s0, s83
	v_writelane_b32 v254, s0, 26
	s_sub_i32 s0, 0, s59
	v_writelane_b32 v254, s0, 27
	v_writelane_b32 v254, s58, 28
	s_sub_i32 s0, s58, s70
	v_writelane_b32 v254, s70, 29
	s_or_b32 s1, s0, 7
	v_writelane_b32 v254, s1, 30
	s_or_b32 s1, s0, 6
	v_writelane_b32 v254, s1, 31
	s_or_b32 s1, s0, 5
	v_writelane_b32 v254, s1, 32
	s_or_b32 s1, s0, 4
	v_writelane_b32 v254, s1, 33
	s_or_b32 s1, s0, 3
	v_writelane_b32 v254, s1, 34
	s_or_b32 s1, s0, 2
	v_writelane_b32 v254, s1, 35
	v_writelane_b32 v254, s0, 36
	s_or_b32 s0, s0, 1
	v_writelane_b32 v254, s0, 37
	s_add_i32 s0, 0, 0x27c20
	v_writelane_b32 v254, s0, 38
	s_add_i32 s0, 0, 0x27c24
	v_writelane_b32 v254, s0, 39
	s_add_i32 s0, 0, 0x14200
	v_writelane_b32 v254, s0, 40
	s_add_i32 s0, 0, 0x27c40
	v_writelane_b32 v254, s0, 41
	s_add_i32 s0, 0, 0x4800
	v_writelane_b32 v254, s0, 42
	s_add_i32 s0, 0, 0x123a0
	v_writelane_b32 v254, s0, 43
	v_writelane_b32 v254, s82, 44
	s_lshl_b64 s[0:1], s[48:49], 1
	s_movk_i32 s58, 0x7fff
	v_writelane_b32 v254, s83, 45
	v_writelane_b32 v254, s0, 46
	s_mov_b64 s[6:7], -1
	s_mov_b32 s70, 0x3e38aa3b
	v_writelane_b32 v254, s1, 47
	v_writelane_b32 v254, s94, 48
	s_mov_b64 s[74:75], 0x2000
	s_mov_b64 s[0:1], 0x8000
	v_writelane_b32 v254, s95, 49
	v_writelane_b32 v254, s80, 50
	s_mov_b64 s[12:13], -1
	s_mov_b32 s26, s83
	v_writelane_b32 v254, s81, 51
	v_writelane_b32 v254, s61, 52
	v_writelane_b32 v254, s84, 53
	v_writelane_b32 v254, s85, 54
	s_branch .LBB0_213

.LBB0_375:
	s_lshl_b32 s6, s6, 6
	s_add_i32 s82, s6, 0x500
	s_lshl_b64 s[8:9], s[82:83], 2
	s_add_u32 s8, s42, s8
	s_addc_u32 s9, s43, s9
	v_mov_b64_e32 v[4:5], s[8:9]
	flat_atomic_add v3, v[4:5], v228 sc0
	v_cvt_f32_u32_e32 v1, v2
	v_sub_u32_e32 v4, 0, v2
	v_rcp_iflag_f32_e32 v1, v1
	s_nop 0
	v_mul_f32_e32 v1, 0x4f7ffffe, v1
	v_cvt_u32_f32_e32 v1, v1
	v_mul_lo_u32 v4, v4, v1
	v_mul_hi_u32 v4, v1, v4
	v_add_u32_e32 v1, v1, v4
	s_waitcnt vmcnt(0) lgkmcnt(0)
	v_mul_hi_u32 v1, v3, v1
	v_mul_lo_u32 v4, v1, v2
	v_sub_u32_e32 v4, v3, v4
	v_cmp_ge_u32_e32 vcc, v4, v2
	v_add_u32_e32 v5, 1, v1
	s_nop 0
	v_cndmask_b32_e32 v1, v1, v5, vcc
	v_sub_u32_e32 v5, v4, v2
	v_cndmask_b32_e32 v4, v4, v5, vcc
	v_cmp_ge_u32_e32 vcc, v4, v2
	v_add_u32_e32 v4, 1, v1
	s_nop 0
	v_cndmask_b32_e32 v1, v1, v4, vcc
	v_add_u32_e32 v4, 1, v3
	v_mad_u64_u32 v[2:3], s[8:9], v2, v1, v[2:3]
	v_cmp_ne_u32_e32 vcc, v4, v2
	s_and_saveexec_b64 s[8:9], vcc
	s_xor_b64 s[8:9], exec, s[8:9]
	s_cbranch_execz .LBB0_388
	s_cmp_eq_u32 s100, 0
	s_cbranch_scc1 .Lnf_1
	s_add_i32 s82, s6, 0x900
	s_lshl_b64 s[10:11], s[82:83], 2
	s_add_u32 s10, s42, s10
	s_addc_u32 s11, s43, s11
	v_mov_b64_e32 v[2:3], s[10:11]
.Lxg_1:
	flat_load_dword v234, v[2:3] sc1
	s_waitcnt vmcnt(0) lgkmcnt(0)
	v_cmp_ne_u32_e32 vcc, v234, v1
	s_cbranch_vccz .Lxg_1
	buffer_inv sc1
	s_waitcnt vmcnt(0)
	s_branch .LBB0_404
.Lnf_1:
	s_add_i32 s82, s6, 0x900
	s_lshl_b64 s[10:11], s[82:83], 2
	s_add_u32 s12, s42, 0x3400
	s_addc_u32 s13, s43, 0
	v_mov_b32_e32 v4, s101
	v_mad_u32_u24 v4, v4, v0, v0
	s_add_i32 s101, s101, 1
	v_mov_b64_e32 v[2:3], s[12:13]
	flat_load_dword v0, v[2:3] sc1
	s_waitcnt vmcnt(0) lgkmcnt(0)
	v_cmp_lt_u32_e32 vcc, v0, v4
	s_and_saveexec_b64 s[10:11], vcc
	s_cbranch_execz .LBB0_387
	s_mov_b32 s7, 1
	s_mov_b64 s[14:15], 0
	s_branch .LBB0_379

.LBB0_388:
	s_andn2_saveexec_b64 s[8:9], s[8:9]
	s_cbranch_execz .LBB0_404
	s_cmp_eq_u32 s100, 0
	s_cbranch_scc1 .Lfl_1
	s_add_i32 s82, s6, 0x900
	s_lshl_b64 s[10:11], s[82:83], 2
	s_add_u32 s10, s42, s10
	s_addc_u32 s11, s43, s11
	v_mov_b64_e32 v[0:1], s[10:11]
	buffer_inv sc1
	flat_atomic_add v[0:1], v228
	s_waitcnt vmcnt(0)
	s_branch .LBB0_404
.Lfl_1:
	s_add_i32 s101, s101, 1
	v_mov_b32_e32 v1, s42
	v_add_co_u32_e32 v2, vcc, 0x3000, v1
	v_mov_b32_e32 v1, s43
	buffer_wbl2 sc1
	s_waitcnt vmcnt(0)
	v_addc_co_u32_e32 v3, vcc, 0, v1, vcc
	flat_atomic_add v1, v[2:3], v228 offset:1024 sc0
	v_cvt_f32_u32_e32 v2, v0
	v_sub_u32_e32 v3, 0, v0
	s_mov_b64 s[12:13], -1
	v_rcp_iflag_f32_e32 v2, v2
	s_nop 0
	v_mul_f32_e32 v2, 0x4f7ffffe, v2
	v_cvt_u32_f32_e32 v2, v2
	v_mul_lo_u32 v3, v3, v2
	v_mul_hi_u32 v3, v2, v3
	v_add_u32_e32 v2, v2, v3
	s_waitcnt vmcnt(0) lgkmcnt(0)
	v_mul_hi_u32 v2, v1, v2
	v_mul_lo_u32 v3, v2, v0
	v_sub_u32_e32 v3, v1, v3
	v_cmp_ge_u32_e32 vcc, v3, v0
	v_add_u32_e32 v4, 1, v2
	s_nop 0
	v_cndmask_b32_e32 v2, v2, v4, vcc
	v_sub_u32_e32 v4, v3, v0
	v_cndmask_b32_e32 v3, v3, v4, vcc
	v_cmp_ge_u32_e32 vcc, v3, v0
	v_add_u32_e32 v3, 1, v2
	s_nop 0
	v_cndmask_b32_e32 v2, v2, v3, vcc
	v_add_u32_e32 v3, 1, v1
	v_mad_u64_u32 v[0:1], s[8:9], v0, v2, v[0:1]
	s_add_u32 s8, s42, 0x3400
	s_addc_u32 s9, s43, 0
	v_cmp_ne_u32_e32 vcc, v3, v0
	v_mov_b32_e32 v3, v0
	v_mov_b64_e32 v[0:1], s[8:9]
	s_and_saveexec_b64 s[10:11], vcc
	s_cbranch_execz .LBB0_401
	v_mov_b64_e32 v[0:1], s[8:9]
	flat_load_dword v0, v[0:1] sc1
	s_mov_b64 s[16:17], 0
	s_waitcnt vmcnt(0) lgkmcnt(0)
	v_cmp_lt_u32_e32 vcc, v0, v3
	s_and_saveexec_b64 s[14:15], vcc
	s_cbranch_execz .LBB0_400
	s_add_u32 s12, s42, 0x200
	s_addc_u32 s13, s43, 0
	s_mov_b32 s7, 1
	s_branch .LBB0_393

.LBB0_757:
	s_lshl_b32 s6, s6, 6
	s_add_i32 s82, s6, 0x500
	s_lshl_b64 s[8:9], s[82:83], 2
	s_add_u32 s8, s54, s8
	s_addc_u32 s9, s55, s9
	v_mov_b64_e32 v[4:5], s[8:9]
	flat_atomic_add v3, v[4:5], v228 sc0
	v_cvt_f32_u32_e32 v1, v2
	v_sub_u32_e32 v4, 0, v2
	v_rcp_iflag_f32_e32 v1, v1
	s_nop 0
	v_mul_f32_e32 v1, 0x4f7ffffe, v1
	v_cvt_u32_f32_e32 v1, v1
	v_mul_lo_u32 v4, v4, v1
	v_mul_hi_u32 v4, v1, v4
	v_add_u32_e32 v1, v1, v4
	s_waitcnt vmcnt(0) lgkmcnt(0)
	v_mul_hi_u32 v1, v3, v1
	v_mul_lo_u32 v4, v1, v2
	v_sub_u32_e32 v4, v3, v4
	v_cmp_ge_u32_e32 vcc, v4, v2
	v_add_u32_e32 v5, 1, v1
	s_nop 0
	v_cndmask_b32_e32 v1, v1, v5, vcc
	v_sub_u32_e32 v5, v4, v2
	v_cndmask_b32_e32 v4, v4, v5, vcc
	v_cmp_ge_u32_e32 vcc, v4, v2
	v_add_u32_e32 v4, 1, v1
	s_nop 0
	v_cndmask_b32_e32 v1, v1, v4, vcc
	v_add_u32_e32 v4, 1, v3
	v_mad_u64_u32 v[2:3], s[8:9], v2, v1, v[2:3]
	v_cmp_ne_u32_e32 vcc, v4, v2
	s_and_saveexec_b64 s[8:9], vcc
	s_xor_b64 s[12:13], exec, s[8:9]
	s_cbranch_execz .LBB0_770
	s_add_i32 s82, s6, 0x900
	s_lshl_b64 s[8:9], s[82:83], 2
	s_add_u32 s16, s54, 0x3400
	s_addc_u32 s17, s55, 0
	v_mov_b32_e32 v4, s101
	v_mad_u32_u24 v4, v4, v0, v0
	s_add_i32 s101, s101, 1
	v_mov_b64_e32 v[2:3], s[16:17]
	flat_load_dword v0, v[2:3] sc1
	s_waitcnt vmcnt(0) lgkmcnt(0)
	v_cmp_lt_u32_e32 vcc, v0, v4
	s_and_saveexec_b64 s[14:15], vcc
	s_cbranch_execz .LBB0_769
	s_mov_b32 s7, 1
	s_mov_b64 s[18:19], 0
	s_branch .LBB0_761

.LBB0_770:
	s_andn2_saveexec_b64 s[12:13], s[12:13]
	s_cbranch_execz .LBB0_786
	s_add_i32 s101, s101, 1
	v_mov_b32_e32 v1, s54
	v_add_co_u32_e32 v2, vcc, 0x3000, v1
	v_mov_b32_e32 v1, s55
	buffer_wbl2 sc1
	s_waitcnt vmcnt(0)
	v_addc_co_u32_e32 v3, vcc, 0, v1, vcc
	flat_atomic_add v1, v[2:3], v228 offset:1024 sc0
	v_cvt_f32_u32_e32 v2, v0
	v_sub_u32_e32 v3, 0, v0
	s_add_u32 s14, s54, 0x3400
	s_addc_u32 s15, s55, 0
	v_rcp_iflag_f32_e32 v2, v2
	s_mov_b64 s[18:19], -1
	v_mul_f32_e32 v2, 0x4f7ffffe, v2
	v_cvt_u32_f32_e32 v2, v2
	v_mul_lo_u32 v3, v3, v2
	v_mul_hi_u32 v3, v2, v3
	v_add_u32_e32 v2, v2, v3
	s_waitcnt vmcnt(0) lgkmcnt(0)
	v_mul_hi_u32 v2, v1, v2
	v_mul_lo_u32 v3, v2, v0
	v_sub_u32_e32 v3, v1, v3
	v_cmp_ge_u32_e32 vcc, v3, v0
	v_add_u32_e32 v4, 1, v2
	s_nop 0
	v_cndmask_b32_e32 v2, v2, v4, vcc
	v_sub_u32_e32 v4, v3, v0
	v_cndmask_b32_e32 v3, v3, v4, vcc
	v_cmp_ge_u32_e32 vcc, v3, v0
	v_add_u32_e32 v3, 1, v2
	s_nop 0
	v_cndmask_b32_e32 v2, v2, v3, vcc
	v_add_u32_e32 v3, 1, v1
	v_mad_u64_u32 v[0:1], s[8:9], v0, v2, v[0:1]
	v_cmp_ne_u32_e32 vcc, v3, v0
	v_mov_b32_e32 v3, v0
	v_mov_b64_e32 v[0:1], s[14:15]
	s_and_saveexec_b64 s[16:17], vcc
	s_cbranch_execz .LBB0_783
	v_mov_b64_e32 v[0:1], s[14:15]
	flat_load_dword v0, v[0:1] sc1
	s_mov_b64 s[22:23], 0
	s_waitcnt vmcnt(0) lgkmcnt(0)
	v_cmp_lt_u32_e32 vcc, v0, v3
	s_and_saveexec_b64 s[20:21], vcc
	s_cbranch_execz .LBB0_782
	s_add_u32 s18, s54, 0x200
	s_addc_u32 s19, s55, 0
	s_mov_b32 s7, 1
	s_branch .LBB0_775

.LBB0_890:
	s_andn2_saveexec_b64 s[8:9], s[12:13]
	s_cbranch_execz .LBB0_906
	s_add_i32 s101, s101, 1
	v_mov_b32_e32 v1, s54
	v_add_co_u32_e32 v2, vcc, 0x3000, v1
	v_mov_b32_e32 v1, s55
	buffer_wbl2 sc1
	s_waitcnt vmcnt(0)
	v_addc_co_u32_e32 v3, vcc, 0, v1, vcc
	flat_atomic_add v1, v[2:3], v228 offset:1024 sc0
	v_cvt_f32_u32_e32 v2, v0
	v_sub_u32_e32 v3, 0, v0
	s_add_u32 s12, s54, 0x3400
	s_addc_u32 s13, s55, 0
	v_rcp_iflag_f32_e32 v2, v2
	s_mov_b64 s[16:17], -1
	v_mul_f32_e32 v2, 0x4f7ffffe, v2
	v_cvt_u32_f32_e32 v2, v2
	v_mul_lo_u32 v3, v3, v2
	v_mul_hi_u32 v3, v2, v3
	v_add_u32_e32 v2, v2, v3
	s_waitcnt vmcnt(0) lgkmcnt(0)
	v_mul_hi_u32 v2, v1, v2
	v_mul_lo_u32 v3, v2, v0
	v_sub_u32_e32 v3, v1, v3
	v_cmp_ge_u32_e32 vcc, v3, v0
	v_add_u32_e32 v4, 1, v2
	s_nop 0
	v_cndmask_b32_e32 v2, v2, v4, vcc
	v_sub_u32_e32 v4, v3, v0
	v_cndmask_b32_e32 v3, v3, v4, vcc
	v_cmp_ge_u32_e32 vcc, v3, v0
	v_add_u32_e32 v3, 1, v2
	s_nop 0
	v_cndmask_b32_e32 v2, v2, v3, vcc
	v_add_u32_e32 v3, 1, v1
	v_mad_u64_u32 v[0:1], s[8:9], v0, v2, v[0:1]
	v_cmp_ne_u32_e32 vcc, v3, v0
	v_mov_b32_e32 v3, v0
	v_mov_b64_e32 v[0:1], s[12:13]
	s_and_saveexec_b64 s[14:15], vcc
	s_cbranch_execz .LBB0_903
	v_mov_b64_e32 v[0:1], s[12:13]
	flat_load_dword v0, v[0:1] sc1
	s_mov_b64 s[20:21], 0
	s_waitcnt vmcnt(0) lgkmcnt(0)
	v_cmp_lt_u32_e32 vcc, v0, v3
	s_and_saveexec_b64 s[18:19], vcc
	s_cbranch_execz .LBB0_902
	s_add_u32 s16, s54, 0x200
	s_addc_u32 s17, s55, 0
	s_mov_b32 s7, 1
	s_branch .LBB0_895

.LBB0_1123:
	s_lshl_b32 s6, s6, 6
	s_add_i32 s82, s6, 0x500
	s_lshl_b64 s[8:9], s[82:83], 2
	s_add_u32 s8, s50, s8
	s_addc_u32 s9, s51, s9
	v_mov_b64_e32 v[4:5], s[8:9]
	flat_atomic_add v3, v[4:5], v228 sc0
	v_cvt_f32_u32_e32 v1, v2
	v_sub_u32_e32 v4, 0, v2
	v_rcp_iflag_f32_e32 v1, v1
	s_nop 0
	v_mul_f32_e32 v1, 0x4f7ffffe, v1
	v_cvt_u32_f32_e32 v1, v1
	v_mul_lo_u32 v4, v4, v1
	v_mul_hi_u32 v4, v1, v4
	v_add_u32_e32 v1, v1, v4
	s_waitcnt vmcnt(0) lgkmcnt(0)
	v_mul_hi_u32 v1, v3, v1
	v_mul_lo_u32 v4, v1, v2
	v_sub_u32_e32 v4, v3, v4
	v_cmp_ge_u32_e32 vcc, v4, v2
	v_add_u32_e32 v5, 1, v1
	s_nop 0
	v_cndmask_b32_e32 v1, v1, v5, vcc
	v_sub_u32_e32 v5, v4, v2
	v_cndmask_b32_e32 v4, v4, v5, vcc
	v_cmp_ge_u32_e32 vcc, v4, v2
	v_add_u32_e32 v4, 1, v1
	s_nop 0
	v_cndmask_b32_e32 v1, v1, v4, vcc
	v_add_u32_e32 v4, 1, v3
	v_mad_u64_u32 v[2:3], s[8:9], v2, v1, v[2:3]
	v_cmp_ne_u32_e32 vcc, v4, v2
	s_and_saveexec_b64 s[8:9], vcc
	s_xor_b64 s[12:13], exec, s[8:9]
	s_cbranch_execz .LBB0_1136
	s_add_i32 s82, s6, 0x900
	s_lshl_b64 s[8:9], s[82:83], 2
	s_add_u32 s16, s50, 0x3400
	s_addc_u32 s17, s51, 0
	v_mov_b32_e32 v4, s101
	v_mad_u32_u24 v4, v4, v0, v0
	s_add_i32 s101, s101, 1
	v_mov_b64_e32 v[2:3], s[16:17]
	flat_load_dword v0, v[2:3] sc1
	s_waitcnt vmcnt(0) lgkmcnt(0)
	v_cmp_lt_u32_e32 vcc, v0, v4
	s_and_saveexec_b64 s[14:15], vcc
	s_cbranch_execz .LBB0_1135
	s_mov_b32 s7, 1
	s_mov_b64 s[18:19], 0
	s_branch .LBB0_1127

.LBB0_1136:
	s_andn2_saveexec_b64 s[8:9], s[12:13]
	s_cbranch_execz .LBB0_1152
	s_add_i32 s101, s101, 1
	v_mov_b32_e32 v1, s50
	v_add_co_u32_e32 v2, vcc, 0x3000, v1
	v_mov_b32_e32 v1, s51
	buffer_wbl2 sc1
	s_waitcnt vmcnt(0)
	v_addc_co_u32_e32 v3, vcc, 0, v1, vcc
	flat_atomic_add v1, v[2:3], v228 offset:1024 sc0
	v_cvt_f32_u32_e32 v2, v0
	v_sub_u32_e32 v3, 0, v0
	s_add_u32 s12, s50, 0x3400
	s_addc_u32 s13, s51, 0
	v_rcp_iflag_f32_e32 v2, v2
	s_mov_b64 s[16:17], -1
	v_mul_f32_e32 v2, 0x4f7ffffe, v2
	v_cvt_u32_f32_e32 v2, v2
	v_mul_lo_u32 v3, v3, v2
	v_mul_hi_u32 v3, v2, v3
	v_add_u32_e32 v2, v2, v3
	s_waitcnt vmcnt(0) lgkmcnt(0)
	v_mul_hi_u32 v2, v1, v2
	v_mul_lo_u32 v3, v2, v0
	v_sub_u32_e32 v3, v1, v3
	v_cmp_ge_u32_e32 vcc, v3, v0
	v_add_u32_e32 v4, 1, v2
	s_nop 0
	v_cndmask_b32_e32 v2, v2, v4, vcc
	v_sub_u32_e32 v4, v3, v0
	v_cndmask_b32_e32 v3, v3, v4, vcc
	v_cmp_ge_u32_e32 vcc, v3, v0
	v_add_u32_e32 v3, 1, v2
	s_nop 0
	v_cndmask_b32_e32 v2, v2, v3, vcc
	v_add_u32_e32 v3, 1, v1
	v_mad_u64_u32 v[0:1], s[8:9], v0, v2, v[0:1]
	v_cmp_ne_u32_e32 vcc, v3, v0
	v_mov_b32_e32 v3, v0
	v_mov_b64_e32 v[0:1], s[12:13]
	s_and_saveexec_b64 s[14:15], vcc
	s_cbranch_execz .LBB0_1149
	v_mov_b64_e32 v[0:1], s[12:13]
	flat_load_dword v0, v[0:1] sc1
	s_mov_b64 s[20:21], 0
	s_waitcnt vmcnt(0) lgkmcnt(0)
	v_cmp_lt_u32_e32 vcc, v0, v3
	s_and_saveexec_b64 s[18:19], vcc
	s_cbranch_execz .LBB0_1148
	s_add_u32 s16, s50, 0x200
	s_addc_u32 s17, s51, 0
	s_mov_b32 s7, 1
	s_branch .LBB0_1141

.LBB0_1238:
	s_lshl_b32 s6, s6, 6
	s_add_i32 s82, s6, 0x500
	s_lshl_b64 s[8:9], s[82:83], 2
	s_add_u32 s8, s50, s8
	s_addc_u32 s9, s51, s9
	v_mov_b64_e32 v[4:5], s[8:9]
	flat_atomic_add v3, v[4:5], v228 sc0
	v_cvt_f32_u32_e32 v1, v2
	v_sub_u32_e32 v4, 0, v2
	v_rcp_iflag_f32_e32 v1, v1
	s_nop 0
	v_mul_f32_e32 v1, 0x4f7ffffe, v1
	v_cvt_u32_f32_e32 v1, v1
	v_mul_lo_u32 v4, v4, v1
	v_mul_hi_u32 v4, v1, v4
	v_add_u32_e32 v1, v1, v4
	s_waitcnt vmcnt(0) lgkmcnt(0)
	v_mul_hi_u32 v1, v3, v1
	v_mul_lo_u32 v4, v1, v2
	v_sub_u32_e32 v4, v3, v4
	v_cmp_ge_u32_e32 vcc, v4, v2
	v_add_u32_e32 v5, 1, v1
	s_nop 0
	v_cndmask_b32_e32 v1, v1, v5, vcc
	v_sub_u32_e32 v5, v4, v2
	v_cndmask_b32_e32 v4, v4, v5, vcc
	v_cmp_ge_u32_e32 vcc, v4, v2
	v_add_u32_e32 v4, 1, v1
	s_nop 0
	v_cndmask_b32_e32 v1, v1, v4, vcc
	v_add_u32_e32 v4, 1, v3
	v_mad_u64_u32 v[2:3], s[8:9], v2, v1, v[2:3]
	v_cmp_ne_u32_e32 vcc, v4, v2
	s_and_saveexec_b64 s[8:9], vcc
	s_xor_b64 s[10:11], exec, s[8:9]
	s_cbranch_execz .LBB0_1251
	s_add_i32 s82, s6, 0x900
	s_lshl_b64 s[8:9], s[82:83], 2
	s_add_u32 s14, s50, 0x3400
	s_addc_u32 s15, s51, 0
	v_mov_b32_e32 v4, s101
	v_mad_u32_u24 v4, v4, v0, v0
	s_add_i32 s101, s101, 1
	v_mov_b64_e32 v[2:3], s[14:15]
	flat_load_dword v0, v[2:3] sc1
	s_waitcnt vmcnt(0) lgkmcnt(0)
	v_cmp_lt_u32_e32 vcc, v0, v4
	s_and_saveexec_b64 s[12:13], vcc
	s_cbranch_execz .LBB0_1250
	s_mov_b32 s7, 1
	s_mov_b64 s[16:17], 0
	s_branch .LBB0_1242

.LBB0_1251:
	s_andn2_saveexec_b64 s[8:9], s[10:11]
	s_cbranch_execz .LBB0_1267
	s_add_i32 s101, s101, 1
	v_mov_b32_e32 v1, s50
	v_add_co_u32_e32 v2, vcc, 0x3000, v1
	v_mov_b32_e32 v1, s51
	buffer_wbl2 sc1
	s_waitcnt vmcnt(0)
	v_addc_co_u32_e32 v3, vcc, 0, v1, vcc
	flat_atomic_add v1, v[2:3], v228 offset:1024 sc0
	v_cvt_f32_u32_e32 v2, v0
	v_sub_u32_e32 v3, 0, v0
	s_add_u32 s10, s50, 0x3400
	s_addc_u32 s11, s51, 0
	v_rcp_iflag_f32_e32 v2, v2
	s_mov_b64 s[14:15], -1
	v_mul_f32_e32 v2, 0x4f7ffffe, v2
	v_cvt_u32_f32_e32 v2, v2
	v_mul_lo_u32 v3, v3, v2
	v_mul_hi_u32 v3, v2, v3
	v_add_u32_e32 v2, v2, v3
	s_waitcnt vmcnt(0) lgkmcnt(0)
	v_mul_hi_u32 v2, v1, v2
	v_mul_lo_u32 v3, v2, v0
	v_sub_u32_e32 v3, v1, v3
	v_cmp_ge_u32_e32 vcc, v3, v0
	v_add_u32_e32 v4, 1, v2
	s_nop 0
	v_cndmask_b32_e32 v2, v2, v4, vcc
	v_sub_u32_e32 v4, v3, v0
	v_cndmask_b32_e32 v3, v3, v4, vcc
	v_cmp_ge_u32_e32 vcc, v3, v0
	v_add_u32_e32 v3, 1, v2
	s_nop 0
	v_cndmask_b32_e32 v2, v2, v3, vcc
	v_add_u32_e32 v3, 1, v1
	v_mad_u64_u32 v[0:1], s[8:9], v0, v2, v[0:1]
	v_cmp_ne_u32_e32 vcc, v3, v0
	v_mov_b32_e32 v3, v0
	v_mov_b64_e32 v[0:1], s[10:11]
	s_and_saveexec_b64 s[12:13], vcc
	s_cbranch_execz .LBB0_1264
	v_mov_b64_e32 v[0:1], s[10:11]
	flat_load_dword v0, v[0:1] sc1
	s_mov_b64 s[18:19], 0
	s_waitcnt vmcnt(0) lgkmcnt(0)
	v_cmp_lt_u32_e32 vcc, v0, v3
	s_and_saveexec_b64 s[16:17], vcc
	s_cbranch_execz .LBB0_1263
	s_add_u32 s14, s50, 0x200
	s_addc_u32 s15, s51, 0
	s_mov_b32 s7, 1
	s_branch .LBB0_1256

.LBB0_1316:
	s_lshl_b32 s6, s6, 6
	s_add_i32 s82, s6, 0x500
	s_lshl_b64 s[8:9], s[82:83], 2
	s_add_u32 s8, s54, s8
	s_addc_u32 s9, s55, s9
	v_mov_b64_e32 v[4:5], s[8:9]
	flat_atomic_add v3, v[4:5], v228 sc0
	v_cvt_f32_u32_e32 v1, v2
	v_sub_u32_e32 v4, 0, v2
	v_rcp_iflag_f32_e32 v1, v1
	s_nop 0
	v_mul_f32_e32 v1, 0x4f7ffffe, v1
	v_cvt_u32_f32_e32 v1, v1
	v_mul_lo_u32 v4, v4, v1
	v_mul_hi_u32 v4, v1, v4
	v_add_u32_e32 v1, v1, v4
	s_waitcnt vmcnt(0) lgkmcnt(0)
	v_mul_hi_u32 v1, v3, v1
	v_mul_lo_u32 v4, v1, v2
	v_sub_u32_e32 v4, v3, v4
	v_cmp_ge_u32_e32 vcc, v4, v2
	v_add_u32_e32 v5, 1, v1
	s_nop 0
	v_cndmask_b32_e32 v1, v1, v5, vcc
	v_sub_u32_e32 v5, v4, v2
	v_cndmask_b32_e32 v4, v4, v5, vcc
	v_cmp_ge_u32_e32 vcc, v4, v2
	v_add_u32_e32 v4, 1, v1
	s_nop 0
	v_cndmask_b32_e32 v1, v1, v4, vcc
	v_add_u32_e32 v4, 1, v3
	v_mad_u64_u32 v[2:3], s[8:9], v2, v1, v[2:3]
	v_cmp_ne_u32_e32 vcc, v4, v2
	s_and_saveexec_b64 s[8:9], vcc
	s_xor_b64 s[12:13], exec, s[8:9]
	s_cbranch_execz .LBB0_1329
	s_cmp_eq_u32 s100, 0
	s_cbranch_scc1 .Lnf_6
	s_add_i32 s82, s6, 0x900
	s_lshl_b64 s[8:9], s[82:83], 2
	s_add_u32 s8, s54, s8
	s_addc_u32 s9, s55, s9
	v_mov_b64_e32 v[2:3], s[8:9]

.Lnf_6:
	s_add_i32 s82, s6, 0x900
	s_lshl_b64 s[8:9], s[82:83], 2
	s_add_u32 s16, s54, 0x3400
	s_addc_u32 s17, s55, 0
	v_mov_b32_e32 v4, s101
	v_mad_u32_u24 v4, v4, v0, v0
	s_add_i32 s101, s101, 1
	v_mov_b64_e32 v[2:3], s[16:17]
	flat_load_dword v0, v[2:3] sc1
	s_waitcnt vmcnt(0) lgkmcnt(0)
	v_cmp_lt_u32_e32 vcc, v0, v4
	s_and_saveexec_b64 s[14:15], vcc
	s_cbranch_execz .LBB0_1328
	s_mov_b32 s7, 1
	s_mov_b64 s[18:19], 0
	s_branch .LBB0_1320

.LBB0_1329:
	s_andn2_saveexec_b64 s[8:9], s[12:13]
	s_cbranch_execz .LBB0_1345
	s_cmp_eq_u32 s100, 0
	s_cbranch_scc1 .Lfl_6
	s_add_i32 s82, s6, 0x900
	s_lshl_b64 s[8:9], s[82:83], 2
	s_add_u32 s8, s54, s8
	s_addc_u32 s9, s55, s9
	v_mov_b64_e32 v[0:1], s[8:9]
	buffer_inv sc1
	flat_atomic_add v[0:1], v228
	s_waitcnt vmcnt(0)
	s_branch .LBB0_1345
.Lfl_6:
	s_add_i32 s101, s101, 1
	v_mov_b32_e32 v1, s54
	v_add_co_u32_e32 v2, vcc, 0x3000, v1
	v_mov_b32_e32 v1, s55
	buffer_wbl2 sc1
	s_waitcnt vmcnt(0)
	v_addc_co_u32_e32 v3, vcc, 0, v1, vcc
	flat_atomic_add v1, v[2:3], v228 offset:1024 sc0
	v_cvt_f32_u32_e32 v2, v0
	v_sub_u32_e32 v3, 0, v0
	s_add_u32 s12, s54, 0x3400
	s_addc_u32 s13, s55, 0
	v_rcp_iflag_f32_e32 v2, v2
	s_mov_b64 s[16:17], -1
	v_mul_f32_e32 v2, 0x4f7ffffe, v2
	v_cvt_u32_f32_e32 v2, v2
	v_mul_lo_u32 v3, v3, v2
	v_mul_hi_u32 v3, v2, v3
	v_add_u32_e32 v2, v2, v3
	s_waitcnt vmcnt(0) lgkmcnt(0)
	v_mul_hi_u32 v2, v1, v2
	v_mul_lo_u32 v3, v2, v0
	v_sub_u32_e32 v3, v1, v3
	v_cmp_ge_u32_e32 vcc, v3, v0
	v_add_u32_e32 v4, 1, v2
	s_nop 0
	v_cndmask_b32_e32 v2, v2, v4, vcc
	v_sub_u32_e32 v4, v3, v0
	v_cndmask_b32_e32 v3, v3, v4, vcc
	v_cmp_ge_u32_e32 vcc, v3, v0
	v_add_u32_e32 v3, 1, v2
	s_nop 0
	v_cndmask_b32_e32 v2, v2, v3, vcc
	v_add_u32_e32 v3, 1, v1
	v_mad_u64_u32 v[0:1], s[8:9], v0, v2, v[0:1]
	v_cmp_ne_u32_e32 vcc, v3, v0
	v_mov_b32_e32 v3, v0
	v_mov_b64_e32 v[0:1], s[12:13]
	s_and_saveexec_b64 s[14:15], vcc
	s_cbranch_execz .LBB0_1342
	v_mov_b64_e32 v[0:1], s[12:13]
	flat_load_dword v0, v[0:1] sc1
	s_mov_b64 s[20:21], 0
	s_waitcnt vmcnt(0) lgkmcnt(0)
	v_cmp_lt_u32_e32 vcc, v0, v3
	s_and_saveexec_b64 s[18:19], vcc
	s_cbranch_execz .LBB0_1341
	s_add_u32 s16, s54, 0x200
	s_addc_u32 s17, s55, 0
	s_mov_b32 s7, 1
	s_branch .LBB0_1334

.Ltramp_7:
	s_getpc_b64 s[98:99]

.LBB0_1402:
	s_cmp_eq_u32 s100, 0
	s_cbranch_scc1 .Lfl_7
	s_add_i32 s82, s6, 0x900
	s_lshl_b64 s[10:11], s[82:83], 2
	s_add_u32 s10, s42, s10
	s_addc_u32 s11, s43, s11
	v_mov_b64_e32 v[0:1], s[10:11]
	buffer_inv sc1
	flat_atomic_add v[0:1], v228
	s_waitcnt vmcnt(0)
	s_branch .Ltramp_7

	.amdhsa_kernel _Z10fwd_kernel6Params
		.amdhsa_group_segment_fixed_size 0
		.amdhsa_private_segment_fixed_size 0
		.amdhsa_kernarg_size 472
		.amdhsa_user_sgpr_count 2
		.amdhsa_user_sgpr_dispatch_ptr 0
		.amdhsa_user_sgpr_queue_ptr 0
		.amdhsa_user_sgpr_kernarg_segment_ptr 1
		.amdhsa_user_sgpr_dispatch_id 0
		.amdhsa_user_sgpr_kernarg_preload_length 0
		.amdhsa_user_sgpr_kernarg_preload_offset 0
		.amdhsa_user_sgpr_private_segment_size 0
		.amdhsa_uses_dynamic_stack 0
		.amdhsa_enable_private_segment 0
		.amdhsa_system_sgpr_workgroup_id_x 1
		.amdhsa_system_sgpr_workgroup_id_y 0
		.amdhsa_system_sgpr_workgroup_id_z 0
		.amdhsa_system_sgpr_workgroup_info 0
		.amdhsa_system_vgpr_workitem_id 0
		.amdhsa_next_free_vgpr 256
		.amdhsa_next_free_sgpr 102
		.amdhsa_accum_offset 256
		.amdhsa_reserve_vcc 1
		.amdhsa_float_round_mode_32 0
		.amdhsa_float_round_mode_16_64 0
		.amdhsa_float_denorm_mode_32 3
		.amdhsa_float_denorm_mode_16_64 3
		.amdhsa_dx10_clamp 1
		.amdhsa_ieee_mode 1
		.amdhsa_fp16_overflow 0
		.amdhsa_tg_split 0
		.amdhsa_exception_fp_ieee_invalid_op 0
		.amdhsa_exception_fp_denorm_src 0
		.amdhsa_exception_fp_ieee_div_zero 0
		.amdhsa_exception_fp_ieee_overflow 0
		.amdhsa_exception_fp_ieee_underflow 0
		.amdhsa_exception_fp_ieee_inexact 0
		.amdhsa_exception_int_div_zero 0
	.end_amdhsa_kernel

amdhsa.kernels:
  - .agpr_count:     0
    .args:
      - .offset:         0
        .size:           216
        .value_kind:     by_value
      - .offset:         216
        .size:           4
        .value_kind:     hidden_block_count_x
      - .offset:         220
        .size:           4
        .value_kind:     hidden_block_count_y
      - .offset:         224
        .size:           4
        .value_kind:     hidden_block_count_z
      - .offset:         228
        .size:           2
        .value_kind:     hidden_group_size_x
      - .offset:         230
        .size:           2
        .value_kind:     hidden_group_size_y
      - .offset:         232
        .size:           2
        .value_kind:     hidden_group_size_z
      - .offset:         234
        .size:           2
        .value_kind:     hidden_remainder_x
      - .offset:         236
        .size:           2
        .value_kind:     hidden_remainder_y
      - .offset:         238
        .size:           2
        .value_kind:     hidden_remainder_z
      - .offset:         256
        .size:           8
        .value_kind:     hidden_global_offset_x
      - .offset:         264
        .size:           8
        .value_kind:     hidden_global_offset_y
      - .offset:         272
        .size:           8
        .value_kind:     hidden_global_offset_z
      - .offset:         280
        .size:           2
        .value_kind:     hidden_grid_dims
      - .offset:         336
        .size:           4
        .value_kind:     hidden_dynamic_lds_size
    .group_segment_fixed_size: 0
    .kernarg_segment_align: 8
    .kernarg_segment_size: 472
    .language:       OpenCL C
    .language_version:
      - 2
      - 0
    .max_flat_workgroup_size: 512
    .name:           _Z10fwd_kernel6Params
    .private_segment_fixed_size: 0
    .sgpr_count:     108
    .sgpr_spill_count: 340
    .symbol:         _Z10fwd_kernel6Params.kd
    .uniform_work_group_size: 1
    .uses_dynamic_stack: false
    .vgpr_count:     256
    .vgpr_spill_count: 0
    .wavefront_size: 64
